# v28 + next work-queue ticket requested from the attention item's tail (atomic round trip off the critical path)
# baseline (speedup 1.0000x reference)
; DI void phase_mixer(const Params& p) {
;   extern __shared__ __attribute__((aligned(16))) char shm_raw[];
;   int* sItem = (int*)(shm_raw + 131072 + 2048);
;   unsigned* ctr = (unsigned*)(p.ws + WS_END);
;   for (;;) {
;     __syncthreads();
;     if (threadIdx.x == 0) *sItem = (int)atomicAdd(ctr, 1u);
;     __syncthreads();
;     const int it = *sItem;
;     if (it >= 48 + 2048) break;
.LBB0_951:
	v_writelane_b32 v236, s48, 7
	v_writelane_b32 v236, s44, 8
	s_nop 1
	v_writelane_b32 v236, s45, 9
	v_writelane_b32 v236, s80, 10
	v_writelane_b32 v236, s41, 11
	v_writelane_b32 v236, s78, 12
	s_nop 1
	v_writelane_b32 v236, s79, 13
	s_or_b64 exec, exec, s[0:1]
	s_add_u32 s82, s58, 0x32000000
	s_addc_u32 s83, s59, 0
	v_cmp_gt_u32_e64 s[0:1], 64, v202
	s_add_u32 s88, s58, 0xa000000
	s_addc_u32 s89, s59, 0
	v_writelane_b32 v236, s0, 14
	v_mov_b32_e32 v193, 0
	v_lshl_add_u64 v[194:195], s[68:69], 0, v[192:193]
	v_writelane_b32 v236, s1, 15
	s_add_u32 s0, s58, 0x12000000
	v_writelane_b32 v236, s0, 16
	s_addc_u32 s0, s59, 0
	v_writelane_b32 v236, s0, 17
	s_add_u32 s0, s58, 0xe000000
	v_writelane_b32 v236, s0, 18
	s_addc_u32 s0, s59, 0
	s_add_u32 s68, s58, 0x2a000000
	s_addc_u32 s69, s59, 0
	s_add_u32 s91, s58, 0x16000000
	s_addc_u32 s92, s59, 0
	s_add_u32 s93, s58, 0x22000000
	v_mbcnt_hi_u32_b32 v204, -1, v145
	s_addc_u32 s94, s59, 0
	s_add_i32 s95, 0, 0x20800
	s_waitcnt lgkmcnt(0)
	v_and_b32_e32 v0, 64, v204
	v_lshl_add_u64 v[196:197], s[70:71], 0, v[192:193]
	s_mov_b32 s71, 0
	s_add_i32 s81, 0, 0x20500
	s_movk_i32 s87, 0xff80
	s_mov_b32 s67, 0x20000
	s_mov_b32 s66, 2.0
	v_mov_b32_e32 v212, 0x358637bd
	s_add_i32 s97, 0, 0x10800
	v_mov_b32_e32 v213, s95
	v_add_u32_e32 v205, 64, v0
	v_xor_b32_e32 v206, 32, v204
	v_xor_b32_e32 v207, 16, v204
	v_xor_b32_e32 v211, 8, v204
	v_xor_b32_e32 v210, 4, v204
	v_xor_b32_e32 v209, 2, v204
	v_xor_b32_e32 v208, 1, v204
	v_mov_b32_e32 v214, 0x7f800000
	v_mov_b32_e32 v215, 0x41b17218
	v_mov_b32_e32 v216, 0x80
	s_barrier
	v_writelane_b32 v236, s0, 19
	s_mov_b32 s32, 0
	s_branch .LBB0_954

; DI void phase_mixer(const Params& p) {
;     ...
;   for (;;) {
;     __syncthreads();
;     if (threadIdx.x == 0) *sItem = (int)atomicAdd(ctr, 1u);
;     __syncthreads();
;     const int it = *sItem;
.LBB0_954:
	s_barrier
	s_and_saveexec_b64 s[0:1], s[84:85]
	s_cbranch_execz .LBB0_958
	s_mov_b64 s[6:7], exec
	v_mbcnt_lo_u32_b32 v0, s6, 0
	v_mbcnt_hi_u32_b32 v0, s7, v0
	v_cmp_eq_u32_e32 vcc, 0, v0
	s_and_saveexec_b64 s[4:5], vcc
	s_cbranch_execz .LBB0_957
	s_cmp_eq_u32 s32, 1
	s_cbranch_scc1 .Lpf_have
	s_bcnt1_i32_b64 s3, s[6:7]
	v_mov_b32_e32 v1, s3
	global_atomic_add v1, v193, v1, s[82:83] sc0
	s_branch .LBB0_957
.Lpf_have:
	s_mov_b32 s32, 0
	s_waitcnt vmcnt(0)
	v_mov_b32_e32 v1, v252

; #define LAS __attribute__((address_space(3)))
; #define PG8_WAIT_V(n) asm volatile("s_waitcnt vmcnt(" #n ")" ::: "memory")
; #define PG8_BAR __builtin_amdgcn_s_barrier()
; #define MFMA32(a, b, c) __builtin_amdgcn_mfma_f32_32x32x16_bf16((a), (b), (c), 0, 0, 0)
; DI void attn_item(const Params& p, const int item) {
;     ...
; #pragma unroll
;     for (int db = 0; db < 4; ++db)
; #pragma unroll
;       for (int s = 0; s < 4; ++s) { const bf16x8 vf = *(const LAS bf16x8*)(vb + db * 4096 + voff[s]); O[db] = MFMA32(vf, pf[s], O[db]); }
;   }
;     ...
;   PG8_WAIT_V(0); PG8_BAR;
;   lsum += __shfl_xor(lsum, 32);
;   const float sc = (c ? lam : 1.f) / lsum;
;   float* ex = (float*)shm_raw;
;   if (c == 1) {
; #pragma unroll
;     for (int db = 0; db < 4; ++db)
; #pragma unroll
;       for (int i = 0; i < 16; ++i) ex[(qs * 128 + 32 * db + (i & 3) + 8 * (i >> 2) + 4 * hl) * 32 + r] = O[db][i] * sc;
;   }
;   __syncthreads();
.LBB0_995:
	s_lshl_b32 s0, s26, 14
	s_add_i32 s0, s0, 0
	v_add_u32_e32 v84, s0, v228
	s_waitcnt vmcnt(0)
	s_barrier
	ds_read_b128 v[64:67], v84 offset:49152
	ds_read_b128 v[68:71], v84 offset:53248
	v_add_u32_e32 v85, s0, v227
	v_add_u32_e32 v86, s0, v226
	v_add_u32_e32 v87, s0, v225
	v_cmp_lt_i32_e32 vcc, v206, v205
	s_cmpk_lt_u32 s13, 0x100
	s_waitcnt lgkmcnt(1)
	v_mfma_f32_32x32x16_bf16 v[48:63], v[64:67], v[120:123], v[48:63]
	ds_read_b128 v[64:67], v85 offset:49152
	ds_read_b128 v[72:75], v85 offset:53248
	s_cselect_b64 s[0:1], -1, 0
	s_cmp_eq_u32 s16, 1
	ds_read_b128 v[76:79], v86 offset:53248
	s_waitcnt lgkmcnt(2)
	v_mfma_f32_32x32x16_bf16 v[48:63], v[64:67], v[112:115], v[48:63]
	ds_read_b128 v[64:67], v86 offset:49152
	s_waitcnt lgkmcnt(0)
	v_mfma_f32_32x32x16_bf16 v[48:63], v[64:67], v[124:127], v[48:63]
	ds_read_b128 v[64:67], v87 offset:49152
	ds_read_b128 v[80:83], v87 offset:53248
	v_mfma_f32_32x32x16_bf16 v[32:47], v[68:71], v[120:123], v[32:47]
	s_waitcnt lgkmcnt(1)
	v_mfma_f32_32x32x16_bf16 v[48:63], v[64:67], v[116:119], v[48:63]
	v_mfma_f32_32x32x16_bf16 v[32:47], v[72:75], v[112:115], v[32:47]
	ds_read_b128 v[64:67], v84 offset:57344
	ds_read_b128 v[70:73], v84 offset:61440
	s_waitcnt lgkmcnt(1)
	v_mfma_f32_32x32x16_bf16 v[16:31], v[64:67], v[120:123], v[16:31]
	v_mfma_f32_32x32x16_bf16 v[32:47], v[76:79], v[124:127], v[32:47]
	ds_read_b128 v[64:67], v85 offset:57344
	ds_read_b128 v[74:77], v85 offset:61440
	s_waitcnt lgkmcnt(1)
	v_mfma_f32_32x32x16_bf16 v[16:31], v[64:67], v[112:115], v[16:31]
	v_mfma_f32_32x32x16_bf16 v[32:47], v[80:83], v[116:119], v[32:47]
	ds_read_b128 v[64:67], v86 offset:57344
	ds_read_b128 v[78:81], v86 offset:61440
	v_mfma_f32_32x32x16_bf16 v[0:15], v[70:73], v[120:123], v[0:15]
	s_waitcnt lgkmcnt(1)
	v_mfma_f32_32x32x16_bf16 v[16:31], v[64:67], v[124:127], v[16:31]
	ds_read_b128 v[64:67], v87 offset:57344
	ds_read_b128 v[82:85], v87 offset:61440
	s_waitcnt vmcnt(0)
	s_barrier
	v_readlane_b32 s98, v236, 5
	v_readlane_b32 s99, v236, 6
	s_mov_b64 s[100:101], exec
	s_nop 3
	s_mov_b64 exec, s[98:99]
	v_mov_b32_e32 v252, 1
	global_atomic_add v252, v193, v252, s[82:83] sc0
	s_mov_b64 exec, s[100:101]
	s_mov_b32 s32, 1
	v_mfma_f32_32x32x16_bf16 v[0:15], v[74:77], v[112:115], v[0:15]
	s_waitcnt lgkmcnt(1)
	v_mfma_f32_32x32x16_bf16 v[16:31], v[64:67], v[116:119], v[16:31]
	v_cndmask_b32_e32 v64, v204, v206, vcc
	v_lshlrev_b32_e32 v69, 2, v64
	ds_bpermute_b32 v64, v69, v231
	v_cndmask_b32_e64 v65, v200, 1.0, s[0:1]
	s_waitcnt lgkmcnt(0)
	v_add_f32_e32 v64, v231, v64
	v_mfma_f32_32x32x16_bf16 v[0:15], v[78:81], v[124:127], v[0:15]
	v_div_scale_f32 v66, s[4:5], v64, v64, v65
	v_rcp_f32_e32 v67, v66
	s_nop 0
	v_fma_f32 v68, -v66, v67, 1.0
	v_mfma_f32_32x32x16_bf16 v[0:15], v[82:85], v[116:119], v[0:15]
	v_fmac_f32_e32 v67, v68, v67
	v_div_scale_f32 v68, vcc, v65, v64, v65
	v_mul_f32_e32 v70, v68, v67
	v_fma_f32 v71, -v66, v70, v68
	v_fmac_f32_e32 v70, v71, v67
	v_fma_f32 v66, -v66, v70, v68
	v_div_fmas_f32 v66, v66, v67, v70
	v_div_fixup_f32 v68, v66, v64, v65
	v_lshlrev_b32_e32 v64, 2, v201
	v_lshl_add_u32 v65, v217, 9, 0
	s_cbranch_scc0 .LBB0_997
	s_lshl_b32 s4, s15, 14
	v_mul_f32_e32 v66, v48, v68
	v_add3_u32 v67, v65, v64, s4
	v_mul_f32_e32 v70, v49, v68
	ds_write2_b32 v67, v66, v70 offset1:32
	v_mul_f32_e32 v66, v50, v68
	v_mul_f32_e32 v70, v51, v68
	ds_write2_b32 v67, v66, v70 offset0:64 offset1:96
	v_mul_f32_e32 v66, v52, v68
	v_mul_f32_e32 v70, v53, v68
	v_add_u32_e32 v71, 0x400, v67
	ds_write2_b32 v71, v66, v70 offset1:32
	v_mul_f32_e32 v66, v54, v68
	v_mul_f32_e32 v70, v55, v68
	ds_write2_b32 v71, v66, v70 offset0:64 offset1:96
	v_mul_f32_e32 v66, v56, v68
	v_mul_f32_e32 v70, v57, v68
	v_add_u32_e32 v71, 0x800, v67
	ds_write2_b32 v71, v66, v70 offset1:32
	v_mul_f32_e32 v66, v58, v68
	v_mul_f32_e32 v70, v59, v68
	ds_write2_b32 v71, v66, v70 offset0:64 offset1:96
	v_mul_f32_e32 v66, v60, v68
	v_mul_f32_e32 v70, v61, v68
	v_add_u32_e32 v71, 0xc00, v67
	ds_write2_b32 v71, v66, v70 offset1:32
	v_mul_f32_e32 v66, v62, v68
	v_mul_f32_e32 v70, v63, v68
	ds_write2_b32 v71, v66, v70 offset0:64 offset1:96
	v_mul_f32_e32 v66, v32, v68
	v_mul_f32_e32 v70, v33, v68
	v_add_u32_e32 v71, 0x1000, v67
	ds_write2_b32 v71, v66, v70 offset1:32
	v_mul_f32_e32 v66, v34, v68
	v_mul_f32_e32 v70, v35, v68
	ds_write2_b32 v71, v66, v70 offset0:64 offset1:96
	v_mul_f32_e32 v66, v36, v68
	v_mul_f32_e32 v70, v37, v68
	v_add_u32_e32 v71, 0x1400, v67
	ds_write2_b32 v71, v66, v70 offset1:32
	v_mul_f32_e32 v66, v38, v68
	v_mul_f32_e32 v70, v39, v68
	ds_write2_b32 v71, v66, v70 offset0:64 offset1:96
	v_mul_f32_e32 v66, v40, v68
	v_mul_f32_e32 v70, v41, v68
	v_add_u32_e32 v71, 0x1800, v67
	ds_write2_b32 v71, v66, v70 offset1:32
	v_mul_f32_e32 v66, v42, v68
	v_mul_f32_e32 v70, v43, v68
	ds_write2_b32 v71, v66, v70 offset0:64 offset1:96
	v_mul_f32_e32 v66, v44, v68
	v_mul_f32_e32 v70, v45, v68
	v_add_u32_e32 v71, 0x1c00, v67
	ds_write2_b32 v71, v66, v70 offset1:32
	v_mul_f32_e32 v66, v46, v68
	v_mul_f32_e32 v70, v47, v68
	ds_write2_b32 v71, v66, v70 offset0:64 offset1:96
	v_mul_f32_e32 v66, v16, v68
	v_mul_f32_e32 v70, v17, v68
	v_add_u32_e32 v71, 0x2000, v67
	ds_write2_b32 v71, v66, v70 offset1:32
	v_mul_f32_e32 v66, v18, v68
	v_mul_f32_e32 v70, v19, v68
	ds_write2_b32 v71, v66, v70 offset0:64 offset1:96
	v_mul_f32_e32 v66, v20, v68
	v_mul_f32_e32 v70, v21, v68
	v_add_u32_e32 v71, 0x2400, v67
	ds_write2_b32 v71, v66, v70 offset1:32
	v_mul_f32_e32 v66, v22, v68
	v_mul_f32_e32 v70, v23, v68
	ds_write2_b32 v71, v66, v70 offset0:64 offset1:96
	v_mul_f32_e32 v66, v24, v68
	v_mul_f32_e32 v70, v25, v68
	v_add_u32_e32 v71, 0x2800, v67
	ds_write2_b32 v71, v66, v70 offset1:32
	v_mul_f32_e32 v66, v26, v68
	v_mul_f32_e32 v70, v27, v68
	ds_write2_b32 v71, v66, v70 offset0:64 offset1:96
	v_mul_f32_e32 v66, v28, v68
	v_mul_f32_e32 v70, v29, v68
	v_add_u32_e32 v71, 0x2c00, v67
	ds_write2_b32 v71, v66, v70 offset1:32
	v_mul_f32_e32 v66, v30, v68
	v_mul_f32_e32 v70, v31, v68
	ds_write2_b32 v71, v66, v70 offset0:64 offset1:96
	v_mul_f32_e32 v66, v0, v68
	v_mul_f32_e32 v70, v1, v68
	v_add_u32_e32 v71, 0x3000, v67
	ds_write2_b32 v71, v66, v70 offset1:32
	v_mul_f32_e32 v66, v2, v68
	v_mul_f32_e32 v70, v3, v68
	ds_write2_b32 v71, v66, v70 offset0:64 offset1:96
	v_mul_f32_e32 v66, v4, v68
	v_mul_f32_e32 v70, v5, v68
	v_add_u32_e32 v71, 0x3400, v67
	ds_write2_b32 v71, v66, v70 offset1:32
	v_mul_f32_e32 v66, v6, v68
	v_mul_f32_e32 v70, v7, v68
	ds_write2_b32 v71, v66, v70 offset0:64 offset1:96
	v_mul_f32_e32 v66, v8, v68
	v_mul_f32_e32 v70, v9, v68
	v_add_u32_e32 v71, 0x3800, v67
	ds_write2_b32 v71, v66, v70 offset1:32
	v_mul_f32_e32 v66, v10, v68
	v_mul_f32_e32 v70, v11, v68
	ds_write2_b32 v71, v66, v70 offset0:64 offset1:96
	v_mul_f32_e32 v66, v12, v68
	v_mul_f32_e32 v70, v13, v68
	v_add_u32_e32 v67, 0x3c00, v67
	ds_write2_b32 v67, v66, v70 offset1:32
	v_mul_f32_e32 v66, v14, v68
	v_mul_f32_e32 v70, v15, v68
	ds_write2_b32 v67, v66, v70 offset0:64 offset1:96

; __global__ void __launch_bounds__(512, 2) mega(Params p) {
	.amdhsa_kernel _Z4mega6Params
		.amdhsa_group_segment_fixed_size 0
		.amdhsa_private_segment_fixed_size 0
		.amdhsa_kernarg_size 392
		.amdhsa_user_sgpr_count 2
		.amdhsa_user_sgpr_dispatch_ptr 0
		.amdhsa_user_sgpr_queue_ptr 0
		.amdhsa_user_sgpr_kernarg_segment_ptr 1
		.amdhsa_user_sgpr_dispatch_id 0
		.amdhsa_user_sgpr_kernarg_preload_length 0
		.amdhsa_user_sgpr_kernarg_preload_offset 0
		.amdhsa_user_sgpr_private_segment_size 0
		.amdhsa_uses_dynamic_stack 0
		.amdhsa_enable_private_segment 0
		.amdhsa_system_sgpr_workgroup_id_x 1
		.amdhsa_system_sgpr_workgroup_id_y 0
		.amdhsa_system_sgpr_workgroup_id_z 0
		.amdhsa_system_sgpr_workgroup_info 0
		.amdhsa_system_vgpr_workitem_id 2
		.amdhsa_next_free_vgpr 256
		.amdhsa_next_free_sgpr 102
		.amdhsa_accum_offset 256
		.amdhsa_reserve_vcc 1
		.amdhsa_float_round_mode_32 0
		.amdhsa_float_round_mode_16_64 0
		.amdhsa_float_denorm_mode_32 3
		.amdhsa_float_denorm_mode_16_64 3
		.amdhsa_dx10_clamp 1
		.amdhsa_ieee_mode 1
		.amdhsa_fp16_overflow 0
		.amdhsa_tg_split 0
		.amdhsa_exception_fp_ieee_invalid_op 0
		.amdhsa_exception_fp_denorm_src 0
		.amdhsa_exception_fp_ieee_div_zero 0
		.amdhsa_exception_fp_ieee_overflow 0
		.amdhsa_exception_fp_ieee_underflow 0
		.amdhsa_exception_fp_ieee_inexact 0
		.amdhsa_exception_int_div_zero 0
	.end_amdhsa_kernel

; __global__ void __launch_bounds__(512, 2) mega(Params p) {
amdhsa.kernels:
  - .agpr_count:     0
    .args:
      - .offset:         0
        .size:           136
        .value_kind:     by_value
      - .offset:         136
        .size:           4
        .value_kind:     hidden_block_count_x
      - .offset:         140
        .size:           4
        .value_kind:     hidden_block_count_y
      - .offset:         144
        .size:           4
        .value_kind:     hidden_block_count_z
      - .offset:         148
        .size:           2
        .value_kind:     hidden_group_size_x
      - .offset:         150
        .size:           2
        .value_kind:     hidden_group_size_y
      - .offset:         152
        .size:           2
        .value_kind:     hidden_group_size_z
      - .offset:         154
        .size:           2
        .value_kind:     hidden_remainder_x
      - .offset:         156
        .size:           2
        .value_kind:     hidden_remainder_y
      - .offset:         158
        .size:           2
        .value_kind:     hidden_remainder_z
      - .offset:         176
        .size:           8
        .value_kind:     hidden_global_offset_x
      - .offset:         184
        .size:           8
        .value_kind:     hidden_global_offset_y
      - .offset:         192
        .size:           8
        .value_kind:     hidden_global_offset_z
      - .offset:         200
        .size:           2
        .value_kind:     hidden_grid_dims
      - .offset:         224
        .size:           8
        .value_kind:     hidden_multigrid_sync_arg
      - .offset:         256
        .size:           4
        .value_kind:     hidden_dynamic_lds_size
    .group_segment_fixed_size: 0
    .kernarg_segment_align: 8
    .kernarg_segment_size: 392
    .language:       OpenCL C
    .language_version:
      - 2
      - 0
    .max_flat_workgroup_size: 512
    .name:           _Z4mega6Params
    .private_segment_fixed_size: 0
    .sgpr_count:     108
    .sgpr_spill_count: 20
    .symbol:         _Z4mega6Params.kd
    .uniform_work_group_size: 1
    .uses_dynamic_stack: false
    .vgpr_count:     256
    .vgpr_spill_count: 0
    .wavefront_size: 64
